# stack8 + LDS reads of the weight-transpose helper pipelined (4 per block)
# speedup vs baseline: 1.0042x; 1.0042x over previous
; #define LAS __attribute__((address_space(3)))
; #define LDS_WAIT() asm volatile("s_waitcnt lgkmcnt(0)" ::: "memory")
; __device__ __forceinline__ unsigned pk2(float lo, float hi) { return pg8::cvt_pk_bf16(lo, hi); }
; __device__ __forceinline__ void p0_tr(const float* __restrict__ W, int K, int N, bf16* WT, int rstride, int roff, LAS float* scr, int item, int lane, const float* gk = nullptr) {
;     ...
; #pragma unroll
;     for (int i = 0; i < 16; ++i)
; #pragma unroll
;         for (int e = 0; e < 4; ++e) scr[(4 * i + kq) * 69 + n4 + e] = v[i][e];
;     LDS_WAIT(); asm volatile("" ::: "memory");
;     const int c = lane & 7;
;     f32x4 ga = {1.f, 1.f, 1.f, 1.f}, gb = {1.f, 1.f, 1.f, 1.f};
;     if (gk) { ga = *(const f32x4*)(gk + k0 + 8 * c); gb = *(const f32x4*)(gk + k0 + 8 * c + 4); }
; #pragma unroll
;     for (int j = 0; j < 8; ++j) { const int n = (lane >> 3) + 8 * j, gn = n0 + n; const LAS float* sp = scr + (8 * c) * 69 + n;
;         u32x4 o; o.x = pk2(sp[0 * 69] * ga[0], sp[1 * 69] * ga[1]); o.y = pk2(sp[2 * 69] * ga[2], sp[3 * 69] * ga[3]); o.z = pk2(sp[4 * 69] * gb[0], sp[5 * 69] * gb[1]); o.w = pk2(sp[6 * 69] * gb[2], sp[7 * 69] * gb[3]);
;         if (gn < N) { const int dr = (gn >> 7) * rstride + roff + (gn & 127); *(u32x4*)(WT + (size_t)dr * K + k0 + 8 * c) = o; } }
.LBB0_402:
	s_or_b64 exec, exec, s[40:41]
	s_waitcnt vmcnt(0)
	ds_write2_b32 v81, v4, v5 offset1:1
	ds_write2_b32 v81, v6, v7 offset0:2 offset1:3
	v_add_u32_e32 v4, 0x450, v81
	ds_write2_b32 v4, v0, v1 offset1:1
	v_add_u32_e32 v0, 0x458, v81
	ds_write2_b32 v0, v2, v3 offset1:1
	v_add_u32_e32 v0, 0x8a0, v81
	ds_write2_b32 v0, v12, v13 offset1:1
	v_add_u32_e32 v0, 0x8a8, v81
	ds_write2_b32 v0, v14, v15 offset1:1
	v_add_u32_e32 v0, 0xcf0, v81
	ds_write2_b32 v0, v8, v9 offset1:1
	v_add_u32_e32 v0, 0xcf8, v81
	ds_write2_b32 v0, v10, v11 offset1:1
	v_add_u32_e32 v0, 0x1140, v81
	ds_write2_b32 v0, v20, v21 offset1:1
	v_add_u32_e32 v0, 0x1148, v81
	ds_write2_b32 v0, v22, v23 offset1:1
	v_add_u32_e32 v0, 0x1590, v81
	ds_write2_b32 v0, v16, v17 offset1:1
	v_add_u32_e32 v0, 0x1598, v81
	ds_write2_b32 v0, v18, v19 offset1:1
	v_add_u32_e32 v0, 0x19e0, v81
	ds_write2_b32 v0, v28, v29 offset1:1
	v_add_u32_e32 v0, 0x19e8, v81
	ds_write2_b32 v0, v30, v31 offset1:1
	v_add_u32_e32 v0, 0x1e30, v81
	ds_write2_b32 v0, v24, v25 offset1:1
	v_add_u32_e32 v0, 0x1e38, v81
	ds_write2_b32 v0, v26, v27 offset1:1
	v_add_u32_e32 v0, 0x2280, v81
	ds_write2_b32 v0, v36, v37 offset1:1
	v_add_u32_e32 v0, 0x2288, v81
	ds_write2_b32 v0, v38, v39 offset1:1
	v_add_u32_e32 v0, 0x26d0, v81
	ds_write2_b32 v0, v32, v33 offset1:1
	v_add_u32_e32 v0, 0x26d8, v81
	ds_write2_b32 v0, v34, v35 offset1:1
	v_add_u32_e32 v0, 0x2b20, v81
	ds_write2_b32 v0, v44, v45 offset1:1
	v_add_u32_e32 v0, 0x2b28, v81
	ds_write2_b32 v0, v46, v47 offset1:1
	v_add_u32_e32 v0, 0x2f70, v81
	ds_write2_b32 v0, v40, v41 offset1:1
	v_add_u32_e32 v0, 0x2f78, v81
	ds_write2_b32 v0, v42, v43 offset1:1
	v_add_u32_e32 v0, 0x33c0, v81
	ds_write2_b32 v0, v52, v53 offset1:1
	v_add_u32_e32 v0, 0x33c8, v81
	ds_write2_b32 v0, v54, v55 offset1:1
	v_add_u32_e32 v0, 0x3810, v81
	ds_write2_b32 v0, v48, v49 offset1:1
	v_add_u32_e32 v0, 0x3818, v81
	ds_write2_b32 v0, v50, v51 offset1:1
	v_add_u32_e32 v0, 0x3c60, v81
	ds_write2_b32 v0, v60, v61 offset1:1
	v_add_u32_e32 v0, 0x3c68, v81
	ds_write2_b32 v0, v62, v63 offset1:1
	v_add_u32_e32 v0, 0x40b0, v81
	ds_write2_b32 v0, v56, v57 offset1:1
	v_add_u32_e32 v0, 0x40b8, v81
	ds_write2_b32 v0, v58, v59 offset1:1
	s_add_u32 s26, s56, s36
	s_waitcnt lgkmcnt(0)
	s_addc_u32 s29, s57, s37
	s_ashr_i32 s39, s38, 31
	s_lshl_b64 s[22:23], s[38:39], 1
	ds_read2_b32 v[96:97], v73 offset1:69
	ds_read2_b32 v[100:101], v73 offset0:138 offset1:207
	s_add_u32 s22, s26, s22
	s_waitcnt lgkmcnt(1)
	v_cvt_pk_bf16_f32 v0, v96, v97
	v_add_u32_e32 v6, 0x400, v73
	ds_read2_b32 v[104:105], v6 offset0:20 offset1:89
	ds_read2_b32 v[108:109], v6 offset0:158 offset1:227
	s_addc_u32 s23, s29, s23
	v_mov_b32_e32 v67, v153
	v_or_b32_e32 v7, s28, v72
	s_waitcnt lgkmcnt(2)
	v_cvt_pk_bf16_f32 v1, v100, v101
	v_lshl_add_u64 v[4:5], s[22:23], 0, v[66:67]
	v_cmp_gt_i32_e32 vcc, s89, v7
	s_waitcnt lgkmcnt(1)
	v_cvt_pk_bf16_f32 v2, v104, v105
	s_waitcnt lgkmcnt(0)
	v_cvt_pk_bf16_f32 v3, v108, v109
	s_and_saveexec_b64 s[36:37], vcc
	s_cbranch_execz .LBB0_404
	v_mul_lo_u32 v8, v7, s5
	v_ashrrev_i32_e32 v9, 31, v8
	v_lshl_add_u64 v[8:9], v[8:9], 1, v[4:5]
	global_store_dwordx4 v[8:9], v[0:3], off
.LBB0_404:
	s_or_b64 exec, exec, s[36:37]
	ds_read2_b32 v[96:97], v73 offset0:8 offset1:77
	ds_read2_b32 v[100:101], v73 offset0:146 offset1:215
	ds_read2_b32 v[104:105], v6 offset0:28 offset1:97
	ds_read2_b32 v[108:109], v6 offset0:166 offset1:235
	s_waitcnt lgkmcnt(3)
	v_cvt_pk_bf16_f32 v0, v96, v97
	v_or_b32_e32 v7, s28, v74
	s_waitcnt lgkmcnt(2)
	v_cvt_pk_bf16_f32 v1, v100, v101
	v_cmp_gt_i32_e32 vcc, s89, v7
	s_waitcnt lgkmcnt(1)
	v_cvt_pk_bf16_f32 v2, v104, v105
	s_waitcnt lgkmcnt(0)
	v_cvt_pk_bf16_f32 v3, v108, v109
	s_and_saveexec_b64 s[36:37], vcc
	s_cbranch_execz .LBB0_406
	v_mul_lo_u32 v8, v7, s5
	v_ashrrev_i32_e32 v9, 31, v8
	v_lshl_add_u64 v[8:9], v[8:9], 1, v[4:5]
	global_store_dwordx4 v[8:9], v[0:3], off
; #define LAS __attribute__((address_space(3)))
; __device__ __forceinline__ unsigned pk2(float lo, float hi) { return pg8::cvt_pk_bf16(lo, hi); }
; __device__ __forceinline__ void p0_tr(const float* __restrict__ W, int K, int N, bf16* WT, int rstride, int roff, LAS float* scr, int item, int lane, const float* gk = nullptr) {
;     ...
;     const int c = lane & 7;
;     f32x4 ga = {1.f, 1.f, 1.f, 1.f}, gb = {1.f, 1.f, 1.f, 1.f};
;     if (gk) { ga = *(const f32x4*)(gk + k0 + 8 * c); gb = *(const f32x4*)(gk + k0 + 8 * c + 4); }
; #pragma unroll
;     for (int j = 0; j < 8; ++j) { const int n = (lane >> 3) + 8 * j, gn = n0 + n; const LAS float* sp = scr + (8 * c) * 69 + n;
;         u32x4 o; o.x = pk2(sp[0 * 69] * ga[0], sp[1 * 69] * ga[1]); o.y = pk2(sp[2 * 69] * ga[2], sp[3 * 69] * ga[3]); o.z = pk2(sp[4 * 69] * gb[0], sp[5 * 69] * gb[1]); o.w = pk2(sp[6 * 69] * gb[2], sp[7 * 69] * gb[3]);
;         if (gn < N) { const int dr = (gn >> 7) * rstride + roff + (gn & 127); *(u32x4*)(WT + (size_t)dr * K + k0 + 8 * c) = o; } }
.LBB0_406:
	s_or_b64 exec, exec, s[36:37]
	ds_read2_b32 v[96:97], v73 offset0:16 offset1:85
	ds_read2_b32 v[100:101], v73 offset0:154 offset1:223
	ds_read2_b32 v[104:105], v6 offset0:36 offset1:105
	ds_read2_b32 v[108:109], v6 offset0:174 offset1:243
	s_waitcnt lgkmcnt(3)
	v_cvt_pk_bf16_f32 v0, v96, v97
	v_or_b32_e32 v7, s28, v75
	s_waitcnt lgkmcnt(2)
	v_cvt_pk_bf16_f32 v1, v100, v101
	v_cmp_gt_i32_e32 vcc, s89, v7
	s_waitcnt lgkmcnt(1)
	v_cvt_pk_bf16_f32 v2, v104, v105
	s_waitcnt lgkmcnt(0)
	v_cvt_pk_bf16_f32 v3, v108, v109
	s_and_saveexec_b64 s[36:37], vcc
	s_cbranch_execz .LBB0_408
	v_mul_lo_u32 v8, v7, s5
	v_ashrrev_i32_e32 v9, 31, v8
	v_lshl_add_u64 v[8:9], v[8:9], 1, v[4:5]
	global_store_dwordx4 v[8:9], v[0:3], off
.LBB0_408:
	s_or_b64 exec, exec, s[36:37]
	ds_read2_b32 v[96:97], v73 offset0:24 offset1:93
	ds_read2_b32 v[100:101], v73 offset0:162 offset1:231
	ds_read2_b32 v[104:105], v6 offset0:44 offset1:113
	ds_read2_b32 v[108:109], v6 offset0:182 offset1:251
	s_waitcnt lgkmcnt(3)
	v_cvt_pk_bf16_f32 v0, v96, v97
	v_or_b32_e32 v7, s28, v76
	s_waitcnt lgkmcnt(2)
	v_cvt_pk_bf16_f32 v1, v100, v101
	v_cmp_gt_i32_e32 vcc, s89, v7
	s_waitcnt lgkmcnt(1)
	v_cvt_pk_bf16_f32 v2, v104, v105
	s_waitcnt lgkmcnt(0)
	v_cvt_pk_bf16_f32 v3, v108, v109
	s_and_saveexec_b64 s[36:37], vcc
	s_cbranch_execz .LBB0_410
	v_mul_lo_u32 v8, v7, s5
	v_ashrrev_i32_e32 v9, 31, v8
	v_lshl_add_u64 v[8:9], v[8:9], 1, v[4:5]
	global_store_dwordx4 v[8:9], v[0:3], off
.LBB0_410:
	s_or_b64 exec, exec, s[36:37]
	ds_read2_b32 v[96:97], v73 offset0:32 offset1:101
	ds_read2_b32 v[100:101], v73 offset0:170 offset1:239
	ds_read2_b32 v[104:105], v6 offset0:52 offset1:121
	s_waitcnt lgkmcnt(2)
	v_cvt_pk_bf16_f32 v0, v96, v97
	v_or_b32_e32 v8, s28, v77
	s_waitcnt lgkmcnt(1)
	v_cvt_pk_bf16_f32 v1, v100, v101
	v_add_u32_e32 v7, 0x600, v73
	ds_read2_b32 v[108:109], v7 offset0:62 offset1:131
	v_cmp_gt_i32_e32 vcc, s89, v8
	s_waitcnt lgkmcnt(1)
	v_cvt_pk_bf16_f32 v2, v104, v105
	s_waitcnt lgkmcnt(0)
	v_cvt_pk_bf16_f32 v3, v108, v109
	s_and_saveexec_b64 s[36:37], vcc
	s_cbranch_execz .LBB0_412
	v_mul_lo_u32 v8, v8, s5
	v_ashrrev_i32_e32 v9, 31, v8
	v_lshl_add_u64 v[8:9], v[8:9], 1, v[4:5]
	global_store_dwordx4 v[8:9], v[0:3], off
.LBB0_412:
	s_or_b64 exec, exec, s[36:37]
	ds_read2_b32 v[96:97], v73 offset0:40 offset1:109
	ds_read2_b32 v[100:101], v73 offset0:178 offset1:247
	ds_read2_b32 v[104:105], v6 offset0:60 offset1:129
	ds_read2_b32 v[108:109], v7 offset0:70 offset1:139
	s_waitcnt lgkmcnt(3)
	v_cvt_pk_bf16_f32 v0, v96, v97
	v_or_b32_e32 v8, s28, v78
	s_waitcnt lgkmcnt(2)
	v_cvt_pk_bf16_f32 v1, v100, v101
	v_cmp_gt_i32_e32 vcc, s89, v8
	s_waitcnt lgkmcnt(1)
	v_cvt_pk_bf16_f32 v2, v104, v105
	s_waitcnt lgkmcnt(0)
	v_cvt_pk_bf16_f32 v3, v108, v109
	s_and_saveexec_b64 s[36:37], vcc
	s_cbranch_execz .LBB0_414
	v_mul_lo_u32 v8, v8, s5
	v_ashrrev_i32_e32 v9, 31, v8
	v_lshl_add_u64 v[8:9], v[8:9], 1, v[4:5]
	global_store_dwordx4 v[8:9], v[0:3], off
.LBB0_414:
	s_or_b64 exec, exec, s[36:37]
	ds_read2_b32 v[96:97], v73 offset0:48 offset1:117
	ds_read2_b32 v[100:101], v73 offset0:186 offset1:255
	ds_read2_b32 v[104:105], v6 offset0:68 offset1:137
	ds_read2_b32 v[108:109], v7 offset0:78 offset1:147
	s_waitcnt lgkmcnt(3)
	v_cvt_pk_bf16_f32 v0, v96, v97
	v_or_b32_e32 v8, s28, v79
	s_waitcnt lgkmcnt(2)
	v_cvt_pk_bf16_f32 v1, v100, v101
	v_cmp_gt_i32_e32 vcc, s89, v8
	s_waitcnt lgkmcnt(1)
	v_cvt_pk_bf16_f32 v2, v104, v105
	s_waitcnt lgkmcnt(0)
	v_cvt_pk_bf16_f32 v3, v108, v109
	s_and_saveexec_b64 s[36:37], vcc
	s_cbranch_execz .LBB0_416
	v_mul_lo_u32 v8, v8, s5
	v_ashrrev_i32_e32 v9, 31, v8
	v_lshl_add_u64 v[8:9], v[8:9], 1, v[4:5]
	global_store_dwordx4 v[8:9], v[0:3], off
.LBB0_416:
	s_or_b64 exec, exec, s[36:37]
	ds_read2_b32 v[96:97], v73 offset0:56 offset1:125
	v_add_u32_e32 v2, 0x200, v73
	ds_read2_b32 v[100:101], v2 offset0:66 offset1:135
	ds_read2_b32 v[104:105], v6 offset0:76 offset1:145
	ds_read2_b32 v[108:109], v7 offset0:86 offset1:155
	s_waitcnt lgkmcnt(3)
	v_cvt_pk_bf16_f32 v0, v96, v97
	s_waitcnt lgkmcnt(2)
	v_cvt_pk_bf16_f32 v1, v100, v101
	v_or_b32_e32 v6, s28, v80
	v_cmp_gt_i32_e32 vcc, s89, v6
	s_waitcnt lgkmcnt(1)
	v_cvt_pk_bf16_f32 v2, v104, v105
	s_waitcnt lgkmcnt(0)
	v_cvt_pk_bf16_f32 v3, v108, v109
	s_and_saveexec_b64 s[28:29], vcc
	s_cbranch_execz .LBB0_365
	v_mul_lo_u32 v6, v6, s5
	v_ashrrev_i32_e32 v7, 31, v6
	v_lshl_add_u64 v[4:5], v[6:7], 1, v[4:5]
	global_store_dwordx4 v[4:5], v[0:3], off
	s_branch .LBB0_365

; #define LAS __attribute__((address_space(3)))
; __device__ __forceinline__ unsigned pk2(float lo, float hi) { return pg8::cvt_pk_bf16(lo, hi); }
; __device__ __forceinline__ void p0_tr(const float* __restrict__ W, int K, int N, bf16* WT, int rstride, int roff, LAS float* scr, int item, int lane, const float* gk = nullptr) {
;     ...
;     const int c = lane & 7;
;     f32x4 ga = {1.f, 1.f, 1.f, 1.f}, gb = {1.f, 1.f, 1.f, 1.f};
;     if (gk) { ga = *(const f32x4*)(gk + k0 + 8 * c); gb = *(const f32x4*)(gk + k0 + 8 * c + 4); }
; #pragma unroll
;     for (int j = 0; j < 8; ++j) { const int n = (lane >> 3) + 8 * j, gn = n0 + n; const LAS float* sp = scr + (8 * c) * 69 + n;
;         u32x4 o; o.x = pk2(sp[0 * 69] * ga[0], sp[1 * 69] * ga[1]); o.y = pk2(sp[2 * 69] * ga[2], sp[3 * 69] * ga[3]); o.z = pk2(sp[4 * 69] * gb[0], sp[5 * 69] * gb[1]); o.w = pk2(sp[6 * 69] * gb[2], sp[7 * 69] * gb[3]);
;         if (gn < N) { const int dr = (gn >> 7) * rstride + roff + (gn & 127); *(u32x4*)(WT + (size_t)dr * K + k0 + 8 * c) = o; } }
.LBB0_457:
	s_or_b64 exec, exec, s[28:29]
	ds_read2_b32 v[96:97], v71 offset0:8 offset1:77
	ds_read2_b32 v[100:101], v71 offset0:146 offset1:215
	ds_read2_b32 v[104:105], v14 offset0:28 offset1:97
	ds_read2_b32 v[108:109], v14 offset0:166 offset1:235
	v_or_b32_e32 v15, s12, v72
	v_cmp_gt_i32_e32 vcc, s5, v15
	s_waitcnt lgkmcnt(3)
	v_mul_f32_e32 v8, v0, v96
	v_mul_f32_e32 v9, v1, v97
	v_cvt_pk_bf16_f32 v8, v8, v9
	s_waitcnt lgkmcnt(2)
	v_mul_f32_e32 v9, v2, v100
	v_mul_f32_e32 v10, v3, v101
	v_cvt_pk_bf16_f32 v9, v9, v10
	s_waitcnt lgkmcnt(1)
	v_mul_f32_e32 v10, v4, v104
	v_mul_f32_e32 v11, v5, v105
	v_cvt_pk_bf16_f32 v10, v10, v11
	s_waitcnt lgkmcnt(0)
	v_mul_f32_e32 v11, v6, v108
	v_mul_f32_e32 v16, v7, v109
	v_cvt_pk_bf16_f32 v11, v11, v16
	s_and_saveexec_b64 s[28:29], vcc
	s_cbranch_execz .LBB0_459
	v_and_b32_e32 v15, 0x4f, v15
	v_or_b32_e32 v16, s15, v15
	v_ashrrev_i32_e32 v17, 31, v16
	v_lshlrev_b64 v[16:17], 12, v[16:17]
	v_lshl_add_u64 v[16:17], v[12:13], 0, v[16:17]
	global_store_dwordx4 v[16:17], v[8:11], off
.LBB0_459:
	s_or_b64 exec, exec, s[28:29]
	ds_read2_b32 v[96:97], v71 offset0:16 offset1:85
	ds_read2_b32 v[100:101], v71 offset0:154 offset1:223
	ds_read2_b32 v[104:105], v14 offset0:36 offset1:105
	ds_read2_b32 v[108:109], v14 offset0:174 offset1:243
	v_or_b32_e32 v15, s12, v73
	v_cmp_gt_i32_e32 vcc, s5, v15
	s_waitcnt lgkmcnt(3)
	v_mul_f32_e32 v8, v0, v96
	v_mul_f32_e32 v9, v1, v97
	v_cvt_pk_bf16_f32 v8, v8, v9
	s_waitcnt lgkmcnt(2)
	v_mul_f32_e32 v9, v2, v100
	v_mul_f32_e32 v10, v3, v101
	v_cvt_pk_bf16_f32 v9, v9, v10
	s_waitcnt lgkmcnt(1)
	v_mul_f32_e32 v10, v4, v104
	v_mul_f32_e32 v11, v5, v105
	v_cvt_pk_bf16_f32 v10, v10, v11
	s_waitcnt lgkmcnt(0)
	v_mul_f32_e32 v11, v6, v108
	v_mul_f32_e32 v16, v7, v109
	v_cvt_pk_bf16_f32 v11, v11, v16
	s_and_saveexec_b64 s[28:29], vcc
	s_cbranch_execz .LBB0_461
	v_and_b32_e32 v15, 0x57, v15
	v_or_b32_e32 v16, s15, v15
	v_ashrrev_i32_e32 v17, 31, v16
	v_lshlrev_b64 v[16:17], 12, v[16:17]
	v_lshl_add_u64 v[16:17], v[12:13], 0, v[16:17]
	global_store_dwordx4 v[16:17], v[8:11], off
.LBB0_461:
	s_or_b64 exec, exec, s[28:29]
	ds_read2_b32 v[96:97], v71 offset0:24 offset1:93
	ds_read2_b32 v[100:101], v71 offset0:162 offset1:231
	ds_read2_b32 v[104:105], v14 offset0:44 offset1:113
	ds_read2_b32 v[108:109], v14 offset0:182 offset1:251
	v_or_b32_e32 v15, s12, v74
	v_cmp_gt_i32_e32 vcc, s5, v15
	s_waitcnt lgkmcnt(3)
	v_mul_f32_e32 v8, v0, v96
	v_mul_f32_e32 v9, v1, v97
	v_cvt_pk_bf16_f32 v8, v8, v9
	s_waitcnt lgkmcnt(2)
	v_mul_f32_e32 v9, v2, v100
	v_mul_f32_e32 v10, v3, v101
	v_cvt_pk_bf16_f32 v9, v9, v10
	s_waitcnt lgkmcnt(1)
	v_mul_f32_e32 v10, v4, v104
	v_mul_f32_e32 v11, v5, v105
	v_cvt_pk_bf16_f32 v10, v10, v11
	s_waitcnt lgkmcnt(0)
	v_mul_f32_e32 v11, v6, v108
	v_mul_f32_e32 v16, v7, v109
	v_cvt_pk_bf16_f32 v11, v11, v16
	s_and_saveexec_b64 s[28:29], vcc
	s_cbranch_execz .LBB0_463
	v_and_b32_e32 v15, 0x5f, v15
	v_or_b32_e32 v16, s15, v15
	v_ashrrev_i32_e32 v17, 31, v16
	v_lshlrev_b64 v[16:17], 12, v[16:17]
	v_lshl_add_u64 v[16:17], v[12:13], 0, v[16:17]
	global_store_dwordx4 v[16:17], v[8:11], off
.LBB0_463:
	s_or_b64 exec, exec, s[28:29]
	ds_read2_b32 v[96:97], v71 offset0:32 offset1:101
	ds_read2_b32 v[100:101], v71 offset0:170 offset1:239
	ds_read2_b32 v[104:105], v14 offset0:52 offset1:121
	v_add_u32_e32 v15, 0x600, v71
	ds_read2_b32 v[108:109], v15 offset0:62 offset1:131
	v_or_b32_e32 v16, s12, v75
	v_cmp_gt_i32_e32 vcc, s5, v16
	s_waitcnt lgkmcnt(3)
	v_mul_f32_e32 v8, v0, v96
	v_mul_f32_e32 v9, v1, v97
	v_cvt_pk_bf16_f32 v8, v8, v9
	s_waitcnt lgkmcnt(2)
	v_mul_f32_e32 v9, v2, v100
	v_mul_f32_e32 v10, v3, v101
	v_cvt_pk_bf16_f32 v9, v9, v10
	s_waitcnt lgkmcnt(1)
	v_mul_f32_e32 v10, v4, v104
	v_mul_f32_e32 v11, v5, v105
	v_cvt_pk_bf16_f32 v10, v10, v11
	s_waitcnt lgkmcnt(0)
	v_mul_f32_e32 v11, v6, v108
	v_mul_f32_e32 v17, v7, v109
	v_cvt_pk_bf16_f32 v11, v11, v17
	s_and_saveexec_b64 s[28:29], vcc
	s_cbranch_execz .LBB0_465
	v_and_b32_e32 v16, 0x67, v16
	v_or_b32_e32 v16, s15, v16
	v_ashrrev_i32_e32 v17, 31, v16
	v_lshlrev_b64 v[16:17], 12, v[16:17]
	v_lshl_add_u64 v[16:17], v[12:13], 0, v[16:17]
	global_store_dwordx4 v[16:17], v[8:11], off
; #define LAS __attribute__((address_space(3)))
; __device__ __forceinline__ unsigned pk2(float lo, float hi) { return pg8::cvt_pk_bf16(lo, hi); }
; __device__ __forceinline__ void p0_tr(const float* __restrict__ W, int K, int N, bf16* WT, int rstride, int roff, LAS float* scr, int item, int lane, const float* gk = nullptr) {
;     ...
;     const int c = lane & 7;
;     f32x4 ga = {1.f, 1.f, 1.f, 1.f}, gb = {1.f, 1.f, 1.f, 1.f};
;     if (gk) { ga = *(const f32x4*)(gk + k0 + 8 * c); gb = *(const f32x4*)(gk + k0 + 8 * c + 4); }
; #pragma unroll
;     for (int j = 0; j < 8; ++j) { const int n = (lane >> 3) + 8 * j, gn = n0 + n; const LAS float* sp = scr + (8 * c) * 69 + n;
;         u32x4 o; o.x = pk2(sp[0 * 69] * ga[0], sp[1 * 69] * ga[1]); o.y = pk2(sp[2 * 69] * ga[2], sp[3 * 69] * ga[3]); o.z = pk2(sp[4 * 69] * gb[0], sp[5 * 69] * gb[1]); o.w = pk2(sp[6 * 69] * gb[2], sp[7 * 69] * gb[3]);
;         if (gn < N) { const int dr = (gn >> 7) * rstride + roff + (gn & 127); *(u32x4*)(WT + (size_t)dr * K + k0 + 8 * c) = o; } }
.LBB0_465:
	s_or_b64 exec, exec, s[28:29]
	ds_read2_b32 v[96:97], v71 offset0:40 offset1:109
	ds_read2_b32 v[100:101], v71 offset0:178 offset1:247
	ds_read2_b32 v[104:105], v14 offset0:60 offset1:129
	ds_read2_b32 v[108:109], v15 offset0:70 offset1:139
	v_or_b32_e32 v16, s12, v76
	v_cmp_gt_i32_e32 vcc, s5, v16
	s_waitcnt lgkmcnt(3)
	v_mul_f32_e32 v8, v0, v96
	v_mul_f32_e32 v9, v1, v97
	v_cvt_pk_bf16_f32 v8, v8, v9
	s_waitcnt lgkmcnt(2)
	v_mul_f32_e32 v9, v2, v100
	v_mul_f32_e32 v10, v3, v101
	v_cvt_pk_bf16_f32 v9, v9, v10
	s_waitcnt lgkmcnt(1)
	v_mul_f32_e32 v10, v4, v104
	v_mul_f32_e32 v11, v5, v105
	v_cvt_pk_bf16_f32 v10, v10, v11
	s_waitcnt lgkmcnt(0)
	v_mul_f32_e32 v11, v6, v108
	v_mul_f32_e32 v17, v7, v109
	v_cvt_pk_bf16_f32 v11, v11, v17
	s_and_saveexec_b64 s[28:29], vcc
	s_cbranch_execz .LBB0_467
	v_and_b32_e32 v16, 0x6f, v16
	v_or_b32_e32 v16, s15, v16
	v_ashrrev_i32_e32 v17, 31, v16
	v_lshlrev_b64 v[16:17], 12, v[16:17]
	v_lshl_add_u64 v[16:17], v[12:13], 0, v[16:17]
	global_store_dwordx4 v[16:17], v[8:11], off
.LBB0_467:
	s_or_b64 exec, exec, s[28:29]
	ds_read2_b32 v[96:97], v71 offset0:48 offset1:117
	ds_read2_b32 v[100:101], v71 offset0:186 offset1:255
	ds_read2_b32 v[104:105], v14 offset0:68 offset1:137
	ds_read2_b32 v[108:109], v15 offset0:78 offset1:147
	v_or_b32_e32 v16, s12, v77
	v_cmp_gt_i32_e32 vcc, s5, v16
	s_waitcnt lgkmcnt(3)
	v_mul_f32_e32 v8, v0, v96
	v_mul_f32_e32 v9, v1, v97
	v_cvt_pk_bf16_f32 v8, v8, v9
	s_waitcnt lgkmcnt(2)
	v_mul_f32_e32 v9, v2, v100
	v_mul_f32_e32 v10, v3, v101
	v_cvt_pk_bf16_f32 v9, v9, v10
	s_waitcnt lgkmcnt(1)
	v_mul_f32_e32 v10, v4, v104
	v_mul_f32_e32 v11, v5, v105
	v_cvt_pk_bf16_f32 v10, v10, v11
	s_waitcnt lgkmcnt(0)
	v_mul_f32_e32 v11, v6, v108
	v_mul_f32_e32 v17, v7, v109
	v_cvt_pk_bf16_f32 v11, v11, v17
	s_and_saveexec_b64 s[28:29], vcc
	s_cbranch_execz .LBB0_469
	v_and_b32_e32 v16, 0x77, v16
	v_or_b32_e32 v16, s15, v16
	v_ashrrev_i32_e32 v17, 31, v16
	v_lshlrev_b64 v[16:17], 12, v[16:17]
	v_lshl_add_u64 v[16:17], v[12:13], 0, v[16:17]
	global_store_dwordx4 v[16:17], v[8:11], off
.LBB0_469:
	s_or_b64 exec, exec, s[28:29]
	ds_read2_b32 v[96:97], v71 offset0:56 offset1:125
	v_add_u32_e32 v10, 0x200, v71
	ds_read2_b32 v[100:101], v10 offset0:66 offset1:135
	ds_read2_b32 v[104:105], v14 offset0:76 offset1:145
	ds_read2_b32 v[108:109], v15 offset0:86 offset1:155
	s_waitcnt lgkmcnt(3)
	v_mul_f32_e32 v0, v0, v96
	v_mul_f32_e32 v1, v1, v97
	v_cvt_pk_bf16_f32 v0, v0, v1
	s_waitcnt lgkmcnt(2)
	v_mul_f32_e32 v1, v2, v100
	v_mul_f32_e32 v2, v3, v101
	v_cvt_pk_bf16_f32 v1, v1, v2
	s_waitcnt lgkmcnt(1)
	v_mul_f32_e32 v2, v4, v104
	v_mul_f32_e32 v3, v5, v105
	v_cvt_pk_bf16_f32 v2, v2, v3
	v_or_b32_e32 v4, s12, v78
	v_cmp_gt_i32_e32 vcc, s5, v4
	s_waitcnt lgkmcnt(0)
	v_mul_f32_e32 v3, v6, v108
	v_mul_f32_e32 v5, v7, v109
	v_cvt_pk_bf16_f32 v3, v3, v5
	s_and_saveexec_b64 s[12:13], vcc
	s_cbranch_execz .LBB0_420
	v_and_b32_e32 v4, 0x7f, v4
	v_or_b32_e32 v4, s15, v4
	v_ashrrev_i32_e32 v5, 31, v4
	v_lshlrev_b64 v[4:5], 12, v[4:5]
	v_lshl_add_u64 v[4:5], v[12:13], 0, v[4:5]
	global_store_dwordx4 v[4:5], v[0:3], off
	s_branch .LBB0_420

; #define LAS __attribute__((address_space(3)))
; __device__ __forceinline__ unsigned pk2(float lo, float hi) { return pg8::cvt_pk_bf16(lo, hi); }
; __device__ __forceinline__ void p0_tr(const float* __restrict__ W, int K, int N, bf16* WT, int rstride, int roff, LAS float* scr, int item, int lane, const float* gk = nullptr) {
;     ...
;     const int c = lane & 7;
;     f32x4 ga = {1.f, 1.f, 1.f, 1.f}, gb = {1.f, 1.f, 1.f, 1.f};
;     if (gk) { ga = *(const f32x4*)(gk + k0 + 8 * c); gb = *(const f32x4*)(gk + k0 + 8 * c + 4); }
; #pragma unroll
;     for (int j = 0; j < 8; ++j) { const int n = (lane >> 3) + 8 * j, gn = n0 + n; const LAS float* sp = scr + (8 * c) * 69 + n;
;         u32x4 o; o.x = pk2(sp[0 * 69] * ga[0], sp[1 * 69] * ga[1]); o.y = pk2(sp[2 * 69] * ga[2], sp[3 * 69] * ga[3]); o.z = pk2(sp[4 * 69] * gb[0], sp[5 * 69] * gb[1]); o.w = pk2(sp[6 * 69] * gb[2], sp[7 * 69] * gb[3]);
;         if (gn < N) { const int dr = (gn >> 7) * rstride + roff + (gn & 127); *(u32x4*)(WT + (size_t)dr * K + k0 + 8 * c) = o; } }
.LBB0_515:
	s_or_b64 exec, exec, s[28:29]
	ds_read2_b32 v[96:97], v73 offset0:8 offset1:77
	ds_read2_b32 v[100:101], v73 offset0:146 offset1:215
	ds_read2_b32 v[104:105], v6 offset0:28 offset1:97
	ds_read2_b32 v[108:109], v6 offset0:166 offset1:235
	s_waitcnt lgkmcnt(3)
	v_cvt_pk_bf16_f32 v0, v96, v97
	v_add_u32_e32 v10, 8, v7
	s_waitcnt lgkmcnt(2)
	v_cvt_pk_bf16_f32 v1, v100, v101
	v_cmp_gt_i32_e32 vcc, s89, v10
	s_waitcnt lgkmcnt(1)
	v_cvt_pk_bf16_f32 v2, v104, v105
	s_waitcnt lgkmcnt(0)
	v_cvt_pk_bf16_f32 v3, v108, v109
	s_and_saveexec_b64 s[28:29], vcc
	s_cbranch_execz .LBB0_517
	v_add_u32_e32 v8, s17, v74
	v_add_u32_e32 v8, 0xb000, v8
	v_ashrrev_i32_e32 v9, 31, v8
	v_lshl_add_u64 v[8:9], v[8:9], 1, v[4:5]
	global_store_dwordx4 v[8:9], v[0:3], off
.LBB0_517:
	s_or_b64 exec, exec, s[28:29]
	ds_read2_b32 v[96:97], v73 offset0:16 offset1:85
	ds_read2_b32 v[100:101], v73 offset0:154 offset1:223
	ds_read2_b32 v[104:105], v6 offset0:36 offset1:105
	ds_read2_b32 v[108:109], v6 offset0:174 offset1:243
	s_waitcnt lgkmcnt(3)
	v_cvt_pk_bf16_f32 v0, v96, v97
	v_add_u32_e32 v10, 16, v7
	s_waitcnt lgkmcnt(2)
	v_cvt_pk_bf16_f32 v1, v100, v101
	v_cmp_gt_i32_e32 vcc, s89, v10
	s_waitcnt lgkmcnt(1)
	v_cvt_pk_bf16_f32 v2, v104, v105
	s_waitcnt lgkmcnt(0)
	v_cvt_pk_bf16_f32 v3, v108, v109
	s_and_saveexec_b64 s[28:29], vcc
	s_cbranch_execz .LBB0_519
	v_add_u32_e32 v8, s17, v74
	v_add_u32_e32 v8, 0x16000, v8
	v_ashrrev_i32_e32 v9, 31, v8
	v_lshl_add_u64 v[8:9], v[8:9], 1, v[4:5]
	global_store_dwordx4 v[8:9], v[0:3], off
.LBB0_519:
	s_or_b64 exec, exec, s[28:29]
	ds_read2_b32 v[96:97], v73 offset0:24 offset1:93
	ds_read2_b32 v[100:101], v73 offset0:162 offset1:231
	ds_read2_b32 v[104:105], v6 offset0:44 offset1:113
	ds_read2_b32 v[108:109], v6 offset0:182 offset1:251
	s_waitcnt lgkmcnt(3)
	v_cvt_pk_bf16_f32 v0, v96, v97
	v_add_u32_e32 v10, 24, v7
	s_waitcnt lgkmcnt(2)
	v_cvt_pk_bf16_f32 v1, v100, v101
	v_cmp_gt_i32_e32 vcc, s89, v10
	s_waitcnt lgkmcnt(1)
	v_cvt_pk_bf16_f32 v2, v104, v105
	s_waitcnt lgkmcnt(0)
	v_cvt_pk_bf16_f32 v3, v108, v109
	s_and_saveexec_b64 s[28:29], vcc
	s_cbranch_execz .LBB0_521
	v_add_u32_e32 v8, s17, v74
	v_add_u32_e32 v8, 0x21000, v8
	v_ashrrev_i32_e32 v9, 31, v8
	v_lshl_add_u64 v[8:9], v[8:9], 1, v[4:5]
	global_store_dwordx4 v[8:9], v[0:3], off
.LBB0_521:
	s_or_b64 exec, exec, s[28:29]
	ds_read2_b32 v[96:97], v73 offset0:32 offset1:101
	ds_read2_b32 v[100:101], v73 offset0:170 offset1:239
	ds_read2_b32 v[104:105], v6 offset0:52 offset1:121
	s_waitcnt lgkmcnt(2)
	v_cvt_pk_bf16_f32 v0, v96, v97
	v_add_u32_e32 v9, 32, v7
	s_waitcnt lgkmcnt(1)
	v_cvt_pk_bf16_f32 v1, v100, v101
	v_add_u32_e32 v8, 0x600, v73
	ds_read2_b32 v[108:109], v8 offset0:62 offset1:131
	v_cmp_gt_i32_e32 vcc, s89, v9
	s_waitcnt lgkmcnt(1)
	v_cvt_pk_bf16_f32 v2, v104, v105
	s_waitcnt lgkmcnt(0)
	v_cvt_pk_bf16_f32 v3, v108, v109
	s_and_saveexec_b64 s[28:29], vcc
	s_cbranch_execz .LBB0_523
	v_add_u32_e32 v9, s17, v74
	v_add_u32_e32 v10, 0x2c000, v9
	v_ashrrev_i32_e32 v11, 31, v10
	v_lshl_add_u64 v[10:11], v[10:11], 1, v[4:5]
	global_store_dwordx4 v[10:11], v[0:3], off
.LBB0_523:
	s_or_b64 exec, exec, s[28:29]
	ds_read2_b32 v[96:97], v73 offset0:40 offset1:109
	ds_read2_b32 v[100:101], v73 offset0:178 offset1:247
	ds_read2_b32 v[104:105], v6 offset0:60 offset1:129
	ds_read2_b32 v[108:109], v8 offset0:70 offset1:139
	s_waitcnt lgkmcnt(3)
	v_cvt_pk_bf16_f32 v0, v96, v97
	v_add_u32_e32 v9, 40, v7
	s_waitcnt lgkmcnt(2)
	v_cvt_pk_bf16_f32 v1, v100, v101
	v_cmp_gt_i32_e32 vcc, s89, v9
	s_waitcnt lgkmcnt(1)
	v_cvt_pk_bf16_f32 v2, v104, v105
	s_waitcnt lgkmcnt(0)
	v_cvt_pk_bf16_f32 v3, v108, v109
	s_and_saveexec_b64 s[28:29], vcc
	s_cbranch_execz .LBB0_525
	v_add_u32_e32 v9, s17, v74
	v_add_u32_e32 v10, 0x37000, v9
	v_ashrrev_i32_e32 v11, 31, v10
	v_lshl_add_u64 v[10:11], v[10:11], 1, v[4:5]
	global_store_dwordx4 v[10:11], v[0:3], off
.LBB0_525:
	s_or_b64 exec, exec, s[28:29]
	ds_read2_b32 v[96:97], v73 offset0:48 offset1:117
	ds_read2_b32 v[100:101], v73 offset0:186 offset1:255
	ds_read2_b32 v[104:105], v6 offset0:68 offset1:137
	ds_read2_b32 v[108:109], v8 offset0:78 offset1:147
	s_waitcnt lgkmcnt(3)
	v_cvt_pk_bf16_f32 v0, v96, v97
	v_add_u32_e32 v9, 48, v7
	s_waitcnt lgkmcnt(2)
	v_cvt_pk_bf16_f32 v1, v100, v101
	v_cmp_gt_i32_e32 vcc, s89, v9
	s_waitcnt lgkmcnt(1)
	v_cvt_pk_bf16_f32 v2, v104, v105
	s_waitcnt lgkmcnt(0)
	v_cvt_pk_bf16_f32 v3, v108, v109
	s_and_saveexec_b64 s[28:29], vcc
	s_cbranch_execz .LBB0_527
	v_add_u32_e32 v9, s17, v74
	v_add_u32_e32 v10, 0x42000, v9
	v_ashrrev_i32_e32 v11, 31, v10
	v_lshl_add_u64 v[10:11], v[10:11], 1, v[4:5]
	global_store_dwordx4 v[10:11], v[0:3], off
.LBB0_527:
	s_or_b64 exec, exec, s[28:29]
	ds_read2_b32 v[96:97], v73 offset0:56 offset1:125
	v_add_u32_e32 v2, 0x200, v73
	ds_read2_b32 v[100:101], v2 offset0:66 offset1:135
	ds_read2_b32 v[104:105], v6 offset0:76 offset1:145
	ds_read2_b32 v[108:109], v8 offset0:86 offset1:155
	s_waitcnt lgkmcnt(3)
	v_cvt_pk_bf16_f32 v0, v96, v97
	s_waitcnt lgkmcnt(2)
	v_cvt_pk_bf16_f32 v1, v100, v101
	v_add_u32_e32 v6, 56, v7
	v_cmp_gt_i32_e32 vcc, s89, v6
	s_waitcnt lgkmcnt(1)
	v_cvt_pk_bf16_f32 v2, v104, v105
	s_waitcnt lgkmcnt(0)
	v_cvt_pk_bf16_f32 v3, v108, v109
	s_and_saveexec_b64 s[28:29], vcc
	s_cbranch_execz .LBB0_476
	v_add_u32_e32 v6, s17, v74
	v_add_u32_e32 v6, 0x4d000, v6
	v_ashrrev_i32_e32 v7, 31, v6
	v_lshl_add_u64 v[4:5], v[6:7], 1, v[4:5]
	global_store_dwordx4 v[4:5], v[0:3], off
	s_branch .LBB0_476

; #define LAS __attribute__((address_space(3)))
; __device__ __forceinline__ unsigned pk2(float lo, float hi) { return pg8::cvt_pk_bf16(lo, hi); }
; __device__ __forceinline__ void p0_tr(const float* __restrict__ W, int K, int N, bf16* WT, int rstride, int roff, LAS float* scr, int item, int lane, const float* gk = nullptr) {
;     ...
;     const int c = lane & 7;
;     f32x4 ga = {1.f, 1.f, 1.f, 1.f}, gb = {1.f, 1.f, 1.f, 1.f};
;     if (gk) { ga = *(const f32x4*)(gk + k0 + 8 * c); gb = *(const f32x4*)(gk + k0 + 8 * c + 4); }
; #pragma unroll
;     for (int j = 0; j < 8; ++j) { const int n = (lane >> 3) + 8 * j, gn = n0 + n; const LAS float* sp = scr + (8 * c) * 69 + n;
;         u32x4 o; o.x = pk2(sp[0 * 69] * ga[0], sp[1 * 69] * ga[1]); o.y = pk2(sp[2 * 69] * ga[2], sp[3 * 69] * ga[3]); o.z = pk2(sp[4 * 69] * gb[0], sp[5 * 69] * gb[1]); o.w = pk2(sp[6 * 69] * gb[2], sp[7 * 69] * gb[3]);
;         if (gn < N) { const int dr = (gn >> 7) * rstride + roff + (gn & 127); *(u32x4*)(WT + (size_t)dr * K + k0 + 8 * c) = o; } }
.LBB0_568:
	s_or_b64 exec, exec, s[10:11]
	ds_read2_b32 v[96:97], v71 offset0:8 offset1:77
	ds_read2_b32 v[100:101], v71 offset0:146 offset1:215
	ds_read2_b32 v[104:105], v14 offset0:28 offset1:97
	ds_read2_b32 v[108:109], v14 offset0:166 offset1:235
	v_add_u32_e32 v16, 8, v15
	v_cmp_gt_i32_e32 vcc, s5, v16
	s_waitcnt lgkmcnt(3)
	v_mul_f32_e32 v8, v4, v96
	v_mul_f32_e32 v9, v5, v97
	v_cvt_pk_bf16_f32 v8, v8, v9
	s_waitcnt lgkmcnt(2)
	v_mul_f32_e32 v9, v6, v100
	v_mul_f32_e32 v10, v7, v101
	v_cvt_pk_bf16_f32 v9, v9, v10
	s_waitcnt lgkmcnt(1)
	v_mul_f32_e32 v10, v0, v104
	v_mul_f32_e32 v11, v1, v105
	v_cvt_pk_bf16_f32 v10, v10, v11
	s_waitcnt lgkmcnt(0)
	v_mul_f32_e32 v11, v2, v108
	v_mul_f32_e32 v17, v3, v109
	v_cvt_pk_bf16_f32 v11, v11, v17
	s_and_saveexec_b64 s[10:11], vcc
	s_cbranch_execz .LBB0_570
	v_and_b32_e32 v16, 0x4f, v16
	v_or_b32_e32 v16, s12, v16
	v_ashrrev_i32_e32 v17, 31, v16
	v_lshlrev_b64 v[16:17], 12, v[16:17]
	v_lshl_add_u64 v[16:17], v[12:13], 0, v[16:17]
	global_store_dwordx4 v[16:17], v[8:11], off
.LBB0_570:
	s_or_b64 exec, exec, s[10:11]
	ds_read2_b32 v[96:97], v71 offset0:16 offset1:85
	ds_read2_b32 v[100:101], v71 offset0:154 offset1:223
	ds_read2_b32 v[104:105], v14 offset0:36 offset1:105
	ds_read2_b32 v[108:109], v14 offset0:174 offset1:243
	v_add_u32_e32 v16, 16, v15
	v_cmp_gt_i32_e32 vcc, s5, v16
	s_waitcnt lgkmcnt(3)
	v_mul_f32_e32 v8, v4, v96
	v_mul_f32_e32 v9, v5, v97
	v_cvt_pk_bf16_f32 v8, v8, v9
	s_waitcnt lgkmcnt(2)
	v_mul_f32_e32 v9, v6, v100
	v_mul_f32_e32 v10, v7, v101
	v_cvt_pk_bf16_f32 v9, v9, v10
	s_waitcnt lgkmcnt(1)
	v_mul_f32_e32 v10, v0, v104
	v_mul_f32_e32 v11, v1, v105
	v_cvt_pk_bf16_f32 v10, v10, v11
	s_waitcnt lgkmcnt(0)
	v_mul_f32_e32 v11, v2, v108
	v_mul_f32_e32 v17, v3, v109
	v_cvt_pk_bf16_f32 v11, v11, v17
	s_and_saveexec_b64 s[10:11], vcc
	s_cbranch_execz .LBB0_572
	v_and_b32_e32 v16, 0x57, v16
	v_or_b32_e32 v16, s12, v16
	v_ashrrev_i32_e32 v17, 31, v16
	v_lshlrev_b64 v[16:17], 12, v[16:17]
	v_lshl_add_u64 v[16:17], v[12:13], 0, v[16:17]
	global_store_dwordx4 v[16:17], v[8:11], off
.LBB0_572:
	s_or_b64 exec, exec, s[10:11]
	ds_read2_b32 v[96:97], v71 offset0:24 offset1:93
	ds_read2_b32 v[100:101], v71 offset0:162 offset1:231
	ds_read2_b32 v[104:105], v14 offset0:44 offset1:113
	ds_read2_b32 v[108:109], v14 offset0:182 offset1:251
	v_add_u32_e32 v16, 24, v15
	v_cmp_gt_i32_e32 vcc, s5, v16
	s_waitcnt lgkmcnt(3)
	v_mul_f32_e32 v8, v4, v96
	v_mul_f32_e32 v9, v5, v97
	v_cvt_pk_bf16_f32 v8, v8, v9
	s_waitcnt lgkmcnt(2)
	v_mul_f32_e32 v9, v6, v100
	v_mul_f32_e32 v10, v7, v101
	v_cvt_pk_bf16_f32 v9, v9, v10
	s_waitcnt lgkmcnt(1)
	v_mul_f32_e32 v10, v0, v104
	v_mul_f32_e32 v11, v1, v105
	v_cvt_pk_bf16_f32 v10, v10, v11
	s_waitcnt lgkmcnt(0)
	v_mul_f32_e32 v11, v2, v108
	v_mul_f32_e32 v17, v3, v109
	v_cvt_pk_bf16_f32 v11, v11, v17
	s_and_saveexec_b64 s[10:11], vcc
	s_cbranch_execz .LBB0_574
	v_and_b32_e32 v16, 0x5f, v16
	v_or_b32_e32 v16, s12, v16
	v_ashrrev_i32_e32 v17, 31, v16
	v_lshlrev_b64 v[16:17], 12, v[16:17]
	v_lshl_add_u64 v[16:17], v[12:13], 0, v[16:17]
	global_store_dwordx4 v[16:17], v[8:11], off
.LBB0_574:
	s_or_b64 exec, exec, s[10:11]
	ds_read2_b32 v[96:97], v71 offset0:32 offset1:101
	ds_read2_b32 v[100:101], v71 offset0:170 offset1:239
	ds_read2_b32 v[104:105], v14 offset0:52 offset1:121
	v_add_u32_e32 v16, 0x600, v71
	ds_read2_b32 v[108:109], v16 offset0:62 offset1:131
	v_add_u32_e32 v17, 32, v15
	v_cmp_gt_i32_e32 vcc, s5, v17
	s_waitcnt lgkmcnt(3)
	v_mul_f32_e32 v8, v4, v96
	v_mul_f32_e32 v9, v5, v97
	v_cvt_pk_bf16_f32 v8, v8, v9
	s_waitcnt lgkmcnt(2)
	v_mul_f32_e32 v9, v6, v100
	v_mul_f32_e32 v10, v7, v101
	v_cvt_pk_bf16_f32 v9, v9, v10
	s_waitcnt lgkmcnt(1)
	v_mul_f32_e32 v10, v0, v104
	v_mul_f32_e32 v11, v1, v105
	v_cvt_pk_bf16_f32 v10, v10, v11
	s_waitcnt lgkmcnt(0)
	v_mul_f32_e32 v11, v2, v108
	v_mul_f32_e32 v18, v3, v109
	v_cvt_pk_bf16_f32 v11, v11, v18
	s_and_saveexec_b64 s[10:11], vcc
	s_cbranch_execz .LBB0_576
	v_and_b32_e32 v17, 0x67, v17
	v_or_b32_e32 v18, s12, v17
	v_ashrrev_i32_e32 v19, 31, v18
	v_lshlrev_b64 v[18:19], 12, v[18:19]
	v_lshl_add_u64 v[18:19], v[12:13], 0, v[18:19]
	global_store_dwordx4 v[18:19], v[8:11], off
; #define LAS __attribute__((address_space(3)))
; __device__ __forceinline__ unsigned pk2(float lo, float hi) { return pg8::cvt_pk_bf16(lo, hi); }
; __device__ __forceinline__ void p0_tr(const float* __restrict__ W, int K, int N, bf16* WT, int rstride, int roff, LAS float* scr, int item, int lane, const float* gk = nullptr) {
;     ...
;     const int c = lane & 7;
;     f32x4 ga = {1.f, 1.f, 1.f, 1.f}, gb = {1.f, 1.f, 1.f, 1.f};
;     if (gk) { ga = *(const f32x4*)(gk + k0 + 8 * c); gb = *(const f32x4*)(gk + k0 + 8 * c + 4); }
; #pragma unroll
;     for (int j = 0; j < 8; ++j) { const int n = (lane >> 3) + 8 * j, gn = n0 + n; const LAS float* sp = scr + (8 * c) * 69 + n;
;         u32x4 o; o.x = pk2(sp[0 * 69] * ga[0], sp[1 * 69] * ga[1]); o.y = pk2(sp[2 * 69] * ga[2], sp[3 * 69] * ga[3]); o.z = pk2(sp[4 * 69] * gb[0], sp[5 * 69] * gb[1]); o.w = pk2(sp[6 * 69] * gb[2], sp[7 * 69] * gb[3]);
;         if (gn < N) { const int dr = (gn >> 7) * rstride + roff + (gn & 127); *(u32x4*)(WT + (size_t)dr * K + k0 + 8 * c) = o; } }
.LBB0_576:
	s_or_b64 exec, exec, s[10:11]
	ds_read2_b32 v[96:97], v71 offset0:40 offset1:109
	ds_read2_b32 v[100:101], v71 offset0:178 offset1:247
	ds_read2_b32 v[104:105], v14 offset0:60 offset1:129
	ds_read2_b32 v[108:109], v16 offset0:70 offset1:139
	v_add_u32_e32 v17, 40, v15
	v_cmp_gt_i32_e32 vcc, s5, v17
	s_waitcnt lgkmcnt(3)
	v_mul_f32_e32 v8, v4, v96
	v_mul_f32_e32 v9, v5, v97
	v_cvt_pk_bf16_f32 v8, v8, v9
	s_waitcnt lgkmcnt(2)
	v_mul_f32_e32 v9, v6, v100
	v_mul_f32_e32 v10, v7, v101
	v_cvt_pk_bf16_f32 v9, v9, v10
	s_waitcnt lgkmcnt(1)
	v_mul_f32_e32 v10, v0, v104
	v_mul_f32_e32 v11, v1, v105
	v_cvt_pk_bf16_f32 v10, v10, v11
	s_waitcnt lgkmcnt(0)
	v_mul_f32_e32 v11, v2, v108
	v_mul_f32_e32 v18, v3, v109
	v_cvt_pk_bf16_f32 v11, v11, v18
	s_and_saveexec_b64 s[10:11], vcc
	s_cbranch_execz .LBB0_578
	v_and_b32_e32 v17, 0x6f, v17
	v_or_b32_e32 v18, s12, v17
	v_ashrrev_i32_e32 v19, 31, v18
	v_lshlrev_b64 v[18:19], 12, v[18:19]
	v_lshl_add_u64 v[18:19], v[12:13], 0, v[18:19]
	global_store_dwordx4 v[18:19], v[8:11], off
.LBB0_578:
	s_or_b64 exec, exec, s[10:11]
	ds_read2_b32 v[96:97], v71 offset0:48 offset1:117
	ds_read2_b32 v[100:101], v71 offset0:186 offset1:255
	ds_read2_b32 v[104:105], v14 offset0:68 offset1:137
	ds_read2_b32 v[108:109], v16 offset0:78 offset1:147
	v_add_u32_e32 v17, 48, v15
	v_cmp_gt_i32_e32 vcc, s5, v17
	s_waitcnt lgkmcnt(3)
	v_mul_f32_e32 v8, v4, v96
	v_mul_f32_e32 v9, v5, v97
	v_cvt_pk_bf16_f32 v8, v8, v9
	s_waitcnt lgkmcnt(2)
	v_mul_f32_e32 v9, v6, v100
	v_mul_f32_e32 v10, v7, v101
	v_cvt_pk_bf16_f32 v9, v9, v10
	s_waitcnt lgkmcnt(1)
	v_mul_f32_e32 v10, v0, v104
	v_mul_f32_e32 v11, v1, v105
	v_cvt_pk_bf16_f32 v10, v10, v11
	s_waitcnt lgkmcnt(0)
	v_mul_f32_e32 v11, v2, v108
	v_mul_f32_e32 v18, v3, v109
	v_cvt_pk_bf16_f32 v11, v11, v18
	s_and_saveexec_b64 s[10:11], vcc
	s_cbranch_execz .LBB0_580
	v_and_b32_e32 v17, 0x77, v17
	v_or_b32_e32 v18, s12, v17
	v_ashrrev_i32_e32 v19, 31, v18
	v_lshlrev_b64 v[18:19], 12, v[18:19]
	v_lshl_add_u64 v[18:19], v[12:13], 0, v[18:19]
	global_store_dwordx4 v[18:19], v[8:11], off
.LBB0_580:
	s_or_b64 exec, exec, s[10:11]
	ds_read2_b32 v[96:97], v71 offset0:56 offset1:125
	v_add_u32_e32 v8, 56, v15
	v_cmp_gt_i32_e32 vcc, s5, v8
	s_waitcnt lgkmcnt(0)
	v_mul_f32_e32 v4, v4, v96
	v_mul_f32_e32 v5, v5, v97
	v_cvt_pk_bf16_f32 v4, v4, v5
	v_add_u32_e32 v5, 0x200, v71
	ds_read2_b32 v[100:101], v5 offset0:66 offset1:135
	ds_read2_b32 v[104:105], v14 offset0:76 offset1:145
	ds_read2_b32 v[108:109], v16 offset0:86 offset1:155
	s_waitcnt lgkmcnt(2)
	v_mul_f32_e32 v5, v6, v100
	v_mul_f32_e32 v6, v7, v101
	v_cvt_pk_bf16_f32 v5, v5, v6
	s_waitcnt lgkmcnt(1)
	v_mul_f32_e32 v0, v0, v104
	v_mul_f32_e32 v1, v1, v105
	v_cvt_pk_bf16_f32 v6, v0, v1
	s_waitcnt lgkmcnt(0)
	v_mul_f32_e32 v0, v2, v108
	v_mul_f32_e32 v1, v3, v109
	v_cvt_pk_bf16_f32 v7, v0, v1
	s_and_saveexec_b64 s[10:11], vcc
	s_cbranch_execz .LBB0_531
	v_and_b32_e32 v0, 0x7f, v8
	v_or_b32_e32 v0, s12, v0
	v_ashrrev_i32_e32 v1, 31, v0
	v_lshlrev_b64 v[0:1], 12, v[0:1]
	v_lshl_add_u64 v[0:1], v[12:13], 0, v[0:1]
	global_store_dwordx4 v[0:1], v[4:7], off
	s_branch .LBB0_531

; #define LAS __attribute__((address_space(3)))
; __device__ __forceinline__ unsigned pk2(float lo, float hi) { return pg8::cvt_pk_bf16(lo, hi); }
; __device__ __forceinline__ void p0_tr(const float* __restrict__ W, int K, int N, bf16* WT, int rstride, int roff, LAS float* scr, int item, int lane, const float* gk = nullptr) {
;     ...
;     for (int j = 0; j < 8; ++j) { const int n = (lane >> 3) + 8 * j, gn = n0 + n; const LAS float* sp = scr + (8 * c) * 69 + n;
;         u32x4 o; o.x = pk2(sp[0 * 69] * ga[0], sp[1 * 69] * ga[1]); o.y = pk2(sp[2 * 69] * ga[2], sp[3 * 69] * ga[3]); o.z = pk2(sp[4 * 69] * gb[0], sp[5 * 69] * gb[1]); o.w = pk2(sp[6 * 69] * gb[2], sp[7 * 69] * gb[3]);
;         if (gn < N) { const int dr = (gn >> 7) * rstride + roff + (gn & 127); *(u32x4*)(WT + (size_t)dr * K + k0 + 8 * c) = o; } }
.LBB0_656:
	s_or_b64 exec, exec, s[8:9]
	ds_read2_b32 v[96:97], v85 offset0:24 offset1:93
	ds_read2_b32 v[100:101], v85 offset0:162 offset1:231
	ds_read2_b32 v[104:105], v14 offset0:44 offset1:113
	ds_read2_b32 v[108:109], v14 offset0:182 offset1:251
	v_or_b32_e32 v15, s0, v88
	v_cmp_gt_u32_e32 vcc, s59, v15
	s_waitcnt lgkmcnt(3)
	v_mul_f32_e32 v8, v0, v96
	v_mul_f32_e32 v9, v1, v97
	v_cvt_pk_bf16_f32 v8, v8, v9
	s_waitcnt lgkmcnt(2)
	v_mul_f32_e32 v9, v2, v100
	v_mul_f32_e32 v10, v3, v101
	v_cvt_pk_bf16_f32 v9, v9, v10
	s_waitcnt lgkmcnt(1)
	v_mul_f32_e32 v10, v4, v104
	v_mul_f32_e32 v11, v5, v105
	v_cvt_pk_bf16_f32 v10, v10, v11
	s_waitcnt lgkmcnt(0)
	v_mul_f32_e32 v11, v6, v108
	v_mul_f32_e32 v16, v7, v109
	v_cvt_pk_bf16_f32 v11, v11, v16
	s_and_saveexec_b64 s[8:9], vcc
	s_cbranch_execz .LBB0_658
	v_lshlrev_b32_e32 v152, 12, v15
	v_lshl_add_u64 v[16:17], v[12:13], 0, v[152:153]
	global_store_dwordx4 v[16:17], v[8:11], off
.LBB0_658:
	s_or_b64 exec, exec, s[8:9]
	ds_read2_b32 v[96:97], v85 offset0:32 offset1:101
	ds_read2_b32 v[100:101], v85 offset0:170 offset1:239
	ds_read2_b32 v[104:105], v14 offset0:52 offset1:121
	v_add_u32_e32 v15, 0x600, v85
	ds_read2_b32 v[108:109], v15 offset0:62 offset1:131
	v_or_b32_e32 v16, s0, v89
	v_cmp_gt_u32_e32 vcc, s59, v16
	s_waitcnt lgkmcnt(3)
	v_mul_f32_e32 v8, v0, v96
	v_mul_f32_e32 v9, v1, v97
	v_cvt_pk_bf16_f32 v8, v8, v9
	s_waitcnt lgkmcnt(2)
	v_mul_f32_e32 v9, v2, v100
	v_mul_f32_e32 v10, v3, v101
	v_cvt_pk_bf16_f32 v9, v9, v10
	s_waitcnt lgkmcnt(1)
	v_mul_f32_e32 v10, v4, v104
	v_mul_f32_e32 v11, v5, v105
	v_cvt_pk_bf16_f32 v10, v10, v11
	s_waitcnt lgkmcnt(0)
	v_mul_f32_e32 v11, v6, v108
	v_mul_f32_e32 v17, v7, v109
	v_cvt_pk_bf16_f32 v11, v11, v17
	s_and_saveexec_b64 s[8:9], vcc
	s_cbranch_execz .LBB0_660
	v_lshlrev_b32_e32 v152, 12, v16
	v_lshl_add_u64 v[16:17], v[12:13], 0, v[152:153]
	global_store_dwordx4 v[16:17], v[8:11], off
.LBB0_660:
	s_or_b64 exec, exec, s[8:9]
	ds_read2_b32 v[96:97], v85 offset0:40 offset1:109
	ds_read2_b32 v[100:101], v85 offset0:178 offset1:247
	ds_read2_b32 v[104:105], v14 offset0:60 offset1:129
	ds_read2_b32 v[108:109], v15 offset0:70 offset1:139
	v_or_b32_e32 v16, s0, v90
	v_cmp_gt_u32_e32 vcc, s59, v16
	s_waitcnt lgkmcnt(3)
	v_mul_f32_e32 v8, v0, v96
	v_mul_f32_e32 v9, v1, v97
	v_cvt_pk_bf16_f32 v8, v8, v9
	s_waitcnt lgkmcnt(2)
	v_mul_f32_e32 v9, v2, v100
	v_mul_f32_e32 v10, v3, v101
	v_cvt_pk_bf16_f32 v9, v9, v10
	s_waitcnt lgkmcnt(1)
	v_mul_f32_e32 v10, v4, v104
	v_mul_f32_e32 v11, v5, v105
	v_cvt_pk_bf16_f32 v10, v10, v11
	s_waitcnt lgkmcnt(0)
	v_mul_f32_e32 v11, v6, v108
	v_mul_f32_e32 v17, v7, v109
	v_cvt_pk_bf16_f32 v11, v11, v17
	s_and_saveexec_b64 s[8:9], vcc
	s_cbranch_execz .LBB0_662
	v_lshlrev_b32_e32 v152, 12, v16
	v_lshl_add_u64 v[16:17], v[12:13], 0, v[152:153]
	global_store_dwordx4 v[16:17], v[8:11], off
.LBB0_662:
	s_or_b64 exec, exec, s[8:9]
	ds_read2_b32 v[96:97], v85 offset0:48 offset1:117
	ds_read2_b32 v[100:101], v85 offset0:186 offset1:255
	ds_read2_b32 v[104:105], v14 offset0:68 offset1:137
	ds_read2_b32 v[108:109], v15 offset0:78 offset1:147
	v_or_b32_e32 v16, s0, v91
	v_cmp_gt_u32_e32 vcc, s59, v16
	s_waitcnt lgkmcnt(3)
	v_mul_f32_e32 v8, v0, v96
	v_mul_f32_e32 v9, v1, v97
	v_cvt_pk_bf16_f32 v8, v8, v9
	s_waitcnt lgkmcnt(2)
	v_mul_f32_e32 v9, v2, v100
	v_mul_f32_e32 v10, v3, v101
	v_cvt_pk_bf16_f32 v9, v9, v10
	s_waitcnt lgkmcnt(1)
	v_mul_f32_e32 v10, v4, v104
	v_mul_f32_e32 v11, v5, v105
	v_cvt_pk_bf16_f32 v10, v10, v11
	s_waitcnt lgkmcnt(0)
	v_mul_f32_e32 v11, v6, v108
	v_mul_f32_e32 v17, v7, v109
	v_cvt_pk_bf16_f32 v11, v11, v17
	s_and_saveexec_b64 s[8:9], vcc
	s_cbranch_execz .LBB0_664
	v_lshlrev_b32_e32 v152, 12, v16
	v_lshl_add_u64 v[16:17], v[12:13], 0, v[152:153]
	global_store_dwordx4 v[16:17], v[8:11], off
.LBB0_664:
	s_or_b64 exec, exec, s[8:9]
	ds_read2_b32 v[96:97], v85 offset0:56 offset1:125
	v_add_u32_e32 v10, 0x200, v85
	ds_read2_b32 v[100:101], v10 offset0:66 offset1:135
	ds_read2_b32 v[104:105], v14 offset0:76 offset1:145
	ds_read2_b32 v[108:109], v15 offset0:86 offset1:155
	s_waitcnt lgkmcnt(3)
	v_mul_f32_e32 v0, v0, v96
	v_mul_f32_e32 v1, v1, v97
	v_cvt_pk_bf16_f32 v0, v0, v1
	s_waitcnt lgkmcnt(2)
	v_mul_f32_e32 v1, v2, v100
	v_mul_f32_e32 v2, v3, v101
	v_cvt_pk_bf16_f32 v1, v1, v2
	s_waitcnt lgkmcnt(1)
	v_mul_f32_e32 v2, v4, v104
	v_mul_f32_e32 v3, v5, v105
	v_cvt_pk_bf16_f32 v2, v2, v3
	v_or_b32_e32 v4, s0, v92
	v_cmp_gt_u32_e32 vcc, s59, v4
	s_waitcnt lgkmcnt(0)
	v_mul_f32_e32 v3, v6, v108
	v_mul_f32_e32 v5, v7, v109
	v_cvt_pk_bf16_f32 v3, v3, v5
	s_and_saveexec_b64 s[8:9], vcc
	s_cbranch_execz .LBB0_666
	v_lshlrev_b32_e32 v152, 12, v4
	v_lshl_add_u64 v[4:5], v[12:13], 0, v[152:153]
	global_store_dwordx4 v[4:5], v[0:3], off

; #define LAS __attribute__((address_space(3)))
; __device__ __forceinline__ unsigned pk2(float lo, float hi) { return pg8::cvt_pk_bf16(lo, hi); }
; __device__ __forceinline__ void p0_tr(const float* __restrict__ W, int K, int N, bf16* WT, int rstride, int roff, LAS float* scr, int item, int lane, const float* gk = nullptr) {
;     ...
;     for (int j = 0; j < 8; ++j) { const int n = (lane >> 3) + 8 * j, gn = n0 + n; const LAS float* sp = scr + (8 * c) * 69 + n;
;         u32x4 o; o.x = pk2(sp[0 * 69] * ga[0], sp[1 * 69] * ga[1]); o.y = pk2(sp[2 * 69] * ga[2], sp[3 * 69] * ga[3]); o.z = pk2(sp[4 * 69] * gb[0], sp[5 * 69] * gb[1]); o.w = pk2(sp[6 * 69] * gb[2], sp[7 * 69] * gb[3]);
;         if (gn < N) { const int dr = (gn >> 7) * rstride + roff + (gn & 127); *(u32x4*)(WT + (size_t)dr * K + k0 + 8 * c) = o; } }
.LBB0_712:
	s_or_b64 exec, exec, s[8:9]
	ds_read2_b32 v[96:97], v85 offset0:8 offset1:77
	ds_read2_b32 v[100:101], v85 offset0:146 offset1:215
	ds_read2_b32 v[104:105], v14 offset0:28 offset1:97
	ds_read2_b32 v[108:109], v14 offset0:166 offset1:235
	v_add_u32_e32 v16, 8, v15
	v_cmp_gt_i32_e32 vcc, s5, v16
	s_waitcnt lgkmcnt(3)
	v_mul_f32_e32 v8, v0, v96
	v_mul_f32_e32 v9, v1, v97
	v_cvt_pk_bf16_f32 v8, v8, v9
	s_waitcnt lgkmcnt(2)
	v_mul_f32_e32 v9, v2, v100
	v_mul_f32_e32 v10, v3, v101
	v_cvt_pk_bf16_f32 v9, v9, v10
	s_waitcnt lgkmcnt(1)
	v_mul_f32_e32 v10, v4, v104
	v_mul_f32_e32 v11, v5, v105
	v_cvt_pk_bf16_f32 v10, v10, v11
	s_waitcnt lgkmcnt(0)
	v_mul_f32_e32 v11, v6, v108
	v_mul_f32_e32 v17, v7, v109
	v_cvt_pk_bf16_f32 v11, v11, v17
	s_and_saveexec_b64 s[8:9], vcc
	s_cbranch_execz .LBB0_714
	v_and_b32_e32 v16, 0x4f, v16
	v_or_b32_e32 v16, s0, v16
	v_ashrrev_i32_e32 v17, 31, v16
	v_lshlrev_b64 v[16:17], 12, v[16:17]
	v_lshl_add_u64 v[16:17], v[12:13], 0, v[16:17]
	global_store_dwordx4 v[16:17], v[8:11], off
.LBB0_714:
	s_or_b64 exec, exec, s[8:9]
	ds_read2_b32 v[96:97], v85 offset0:16 offset1:85
	ds_read2_b32 v[100:101], v85 offset0:154 offset1:223
	ds_read2_b32 v[104:105], v14 offset0:36 offset1:105
	ds_read2_b32 v[108:109], v14 offset0:174 offset1:243
	v_add_u32_e32 v16, 16, v15
	v_cmp_gt_i32_e32 vcc, s5, v16
	s_waitcnt lgkmcnt(3)
	v_mul_f32_e32 v8, v0, v96
	v_mul_f32_e32 v9, v1, v97
	v_cvt_pk_bf16_f32 v8, v8, v9
	s_waitcnt lgkmcnt(2)
	v_mul_f32_e32 v9, v2, v100
	v_mul_f32_e32 v10, v3, v101
	v_cvt_pk_bf16_f32 v9, v9, v10
	s_waitcnt lgkmcnt(1)
	v_mul_f32_e32 v10, v4, v104
	v_mul_f32_e32 v11, v5, v105
	v_cvt_pk_bf16_f32 v10, v10, v11
	s_waitcnt lgkmcnt(0)
	v_mul_f32_e32 v11, v6, v108
	v_mul_f32_e32 v17, v7, v109
	v_cvt_pk_bf16_f32 v11, v11, v17
	s_and_saveexec_b64 s[8:9], vcc
	s_cbranch_execz .LBB0_716
	v_and_b32_e32 v16, 0x57, v16
	v_or_b32_e32 v16, s0, v16
	v_ashrrev_i32_e32 v17, 31, v16
	v_lshlrev_b64 v[16:17], 12, v[16:17]
	v_lshl_add_u64 v[16:17], v[12:13], 0, v[16:17]
	global_store_dwordx4 v[16:17], v[8:11], off
.LBB0_716:
	s_or_b64 exec, exec, s[8:9]
	ds_read2_b32 v[96:97], v85 offset0:24 offset1:93
	ds_read2_b32 v[100:101], v85 offset0:162 offset1:231
	ds_read2_b32 v[104:105], v14 offset0:44 offset1:113
	ds_read2_b32 v[108:109], v14 offset0:182 offset1:251
	v_add_u32_e32 v16, 24, v15
	v_cmp_gt_i32_e32 vcc, s5, v16
	s_waitcnt lgkmcnt(3)
	v_mul_f32_e32 v8, v0, v96
	v_mul_f32_e32 v9, v1, v97
	v_cvt_pk_bf16_f32 v8, v8, v9
	s_waitcnt lgkmcnt(2)
	v_mul_f32_e32 v9, v2, v100
	v_mul_f32_e32 v10, v3, v101
	v_cvt_pk_bf16_f32 v9, v9, v10
	s_waitcnt lgkmcnt(1)
	v_mul_f32_e32 v10, v4, v104
	v_mul_f32_e32 v11, v5, v105
	v_cvt_pk_bf16_f32 v10, v10, v11
	s_waitcnt lgkmcnt(0)
	v_mul_f32_e32 v11, v6, v108
	v_mul_f32_e32 v17, v7, v109
	v_cvt_pk_bf16_f32 v11, v11, v17
	s_and_saveexec_b64 s[8:9], vcc
	s_cbranch_execz .LBB0_718
	v_and_b32_e32 v16, 0x5f, v16
	v_or_b32_e32 v16, s0, v16
	v_ashrrev_i32_e32 v17, 31, v16
	v_lshlrev_b64 v[16:17], 12, v[16:17]
	v_lshl_add_u64 v[16:17], v[12:13], 0, v[16:17]
	global_store_dwordx4 v[16:17], v[8:11], off
.LBB0_718:
	s_or_b64 exec, exec, s[8:9]
	ds_read2_b32 v[96:97], v85 offset0:32 offset1:101
	ds_read2_b32 v[100:101], v85 offset0:170 offset1:239
	ds_read2_b32 v[104:105], v14 offset0:52 offset1:121
	v_add_u32_e32 v16, 0x600, v85
	ds_read2_b32 v[108:109], v16 offset0:62 offset1:131
	v_add_u32_e32 v17, 32, v15
	v_cmp_gt_i32_e32 vcc, s5, v17
	s_waitcnt lgkmcnt(3)
	v_mul_f32_e32 v8, v0, v96
	v_mul_f32_e32 v9, v1, v97
	v_cvt_pk_bf16_f32 v8, v8, v9
	s_waitcnt lgkmcnt(2)
	v_mul_f32_e32 v9, v2, v100
	v_mul_f32_e32 v10, v3, v101
	v_cvt_pk_bf16_f32 v9, v9, v10
	s_waitcnt lgkmcnt(1)
	v_mul_f32_e32 v10, v4, v104
	v_mul_f32_e32 v11, v5, v105
	v_cvt_pk_bf16_f32 v10, v10, v11
	s_waitcnt lgkmcnt(0)
	v_mul_f32_e32 v11, v6, v108
	v_mul_f32_e32 v18, v7, v109
	v_cvt_pk_bf16_f32 v11, v11, v18
	s_and_saveexec_b64 s[8:9], vcc
	s_cbranch_execz .LBB0_720
	v_and_b32_e32 v17, 0x67, v17
	v_or_b32_e32 v18, s0, v17
	v_ashrrev_i32_e32 v19, 31, v18
	v_lshlrev_b64 v[18:19], 12, v[18:19]
	v_lshl_add_u64 v[18:19], v[12:13], 0, v[18:19]
	global_store_dwordx4 v[18:19], v[8:11], off
; #define LAS __attribute__((address_space(3)))
; __device__ __forceinline__ unsigned pk2(float lo, float hi) { return pg8::cvt_pk_bf16(lo, hi); }
; __device__ __forceinline__ void p0_tr(const float* __restrict__ W, int K, int N, bf16* WT, int rstride, int roff, LAS float* scr, int item, int lane, const float* gk = nullptr) {
;     ...
;     for (int j = 0; j < 8; ++j) { const int n = (lane >> 3) + 8 * j, gn = n0 + n; const LAS float* sp = scr + (8 * c) * 69 + n;
;         u32x4 o; o.x = pk2(sp[0 * 69] * ga[0], sp[1 * 69] * ga[1]); o.y = pk2(sp[2 * 69] * ga[2], sp[3 * 69] * ga[3]); o.z = pk2(sp[4 * 69] * gb[0], sp[5 * 69] * gb[1]); o.w = pk2(sp[6 * 69] * gb[2], sp[7 * 69] * gb[3]);
;         if (gn < N) { const int dr = (gn >> 7) * rstride + roff + (gn & 127); *(u32x4*)(WT + (size_t)dr * K + k0 + 8 * c) = o; } }
.LBB0_720:
	s_or_b64 exec, exec, s[8:9]
	ds_read2_b32 v[96:97], v85 offset0:40 offset1:109
	ds_read2_b32 v[100:101], v85 offset0:178 offset1:247
	ds_read2_b32 v[104:105], v14 offset0:60 offset1:129
	ds_read2_b32 v[108:109], v16 offset0:70 offset1:139
	v_add_u32_e32 v17, 40, v15
	v_cmp_gt_i32_e32 vcc, s5, v17
	s_waitcnt lgkmcnt(3)
	v_mul_f32_e32 v8, v0, v96
	v_mul_f32_e32 v9, v1, v97
	v_cvt_pk_bf16_f32 v8, v8, v9
	s_waitcnt lgkmcnt(2)
	v_mul_f32_e32 v9, v2, v100
	v_mul_f32_e32 v10, v3, v101
	v_cvt_pk_bf16_f32 v9, v9, v10
	s_waitcnt lgkmcnt(1)
	v_mul_f32_e32 v10, v4, v104
	v_mul_f32_e32 v11, v5, v105
	v_cvt_pk_bf16_f32 v10, v10, v11
	s_waitcnt lgkmcnt(0)
	v_mul_f32_e32 v11, v6, v108
	v_mul_f32_e32 v18, v7, v109
	v_cvt_pk_bf16_f32 v11, v11, v18
	s_and_saveexec_b64 s[8:9], vcc
	s_cbranch_execz .LBB0_722
	v_and_b32_e32 v17, 0x6f, v17
	v_or_b32_e32 v18, s0, v17
	v_ashrrev_i32_e32 v19, 31, v18
	v_lshlrev_b64 v[18:19], 12, v[18:19]
	v_lshl_add_u64 v[18:19], v[12:13], 0, v[18:19]
	global_store_dwordx4 v[18:19], v[8:11], off
.LBB0_722:
	s_or_b64 exec, exec, s[8:9]
	ds_read2_b32 v[96:97], v85 offset0:48 offset1:117
	ds_read2_b32 v[100:101], v85 offset0:186 offset1:255
	ds_read2_b32 v[104:105], v14 offset0:68 offset1:137
	ds_read2_b32 v[108:109], v16 offset0:78 offset1:147
	v_add_u32_e32 v17, 48, v15
	v_cmp_gt_i32_e32 vcc, s5, v17
	s_waitcnt lgkmcnt(3)
	v_mul_f32_e32 v8, v0, v96
	v_mul_f32_e32 v9, v1, v97
	v_cvt_pk_bf16_f32 v8, v8, v9
	s_waitcnt lgkmcnt(2)
	v_mul_f32_e32 v9, v2, v100
	v_mul_f32_e32 v10, v3, v101
	v_cvt_pk_bf16_f32 v9, v9, v10
	s_waitcnt lgkmcnt(1)
	v_mul_f32_e32 v10, v4, v104
	v_mul_f32_e32 v11, v5, v105
	v_cvt_pk_bf16_f32 v10, v10, v11
	s_waitcnt lgkmcnt(0)
	v_mul_f32_e32 v11, v6, v108
	v_mul_f32_e32 v18, v7, v109
	v_cvt_pk_bf16_f32 v11, v11, v18
	s_and_saveexec_b64 s[8:9], vcc
	s_cbranch_execz .LBB0_724
	v_and_b32_e32 v17, 0x77, v17
	v_or_b32_e32 v18, s0, v17
	v_ashrrev_i32_e32 v19, 31, v18
	v_lshlrev_b64 v[18:19], 12, v[18:19]
	v_lshl_add_u64 v[18:19], v[12:13], 0, v[18:19]
	global_store_dwordx4 v[18:19], v[8:11], off
.LBB0_724:
	s_or_b64 exec, exec, s[8:9]
	ds_read2_b32 v[96:97], v85 offset0:56 offset1:125
	v_add_u32_e32 v10, 0x200, v85
	ds_read2_b32 v[100:101], v10 offset0:66 offset1:135
	ds_read2_b32 v[104:105], v14 offset0:76 offset1:145
	ds_read2_b32 v[108:109], v16 offset0:86 offset1:155
	s_waitcnt lgkmcnt(3)
	v_mul_f32_e32 v0, v0, v96
	v_mul_f32_e32 v1, v1, v97
	v_cvt_pk_bf16_f32 v0, v0, v1
	s_waitcnt lgkmcnt(2)
	v_mul_f32_e32 v1, v2, v100
	v_mul_f32_e32 v2, v3, v101
	v_cvt_pk_bf16_f32 v1, v1, v2
	s_waitcnt lgkmcnt(1)
	v_mul_f32_e32 v2, v4, v104
	v_mul_f32_e32 v3, v5, v105
	v_cvt_pk_bf16_f32 v2, v2, v3
	v_add_u32_e32 v4, 56, v15
	v_cmp_gt_i32_e32 vcc, s5, v4
	s_waitcnt lgkmcnt(0)
	v_mul_f32_e32 v3, v6, v108
	v_mul_f32_e32 v5, v7, v109
	v_cvt_pk_bf16_f32 v3, v3, v5
	s_and_saveexec_b64 s[8:9], vcc
	s_cbranch_execz .LBB0_585
	v_and_b32_e32 v4, 0x7f, v4
	v_or_b32_e32 v4, s0, v4
	v_ashrrev_i32_e32 v5, 31, v4
	v_lshlrev_b64 v[4:5], 12, v[4:5]
	v_lshl_add_u64 v[4:5], v[12:13], 0, v[4:5]
	global_store_dwordx4 v[4:5], v[0:3], off
	s_branch .LBB0_585
